# v22 + dead m0 save/restore and +0 scalar adds removed around the LDS-DMA blocks
# speedup vs baseline: 1.0033x; 1.0033x over previous
; #define ATT_BAR() asm volatile("s_waitcnt lgkmcnt(0)\n\ts_barrier" ::: "memory")
; #define ATT_BAR() asm volatile("s_waitcnt vmcnt(0) lgkmcnt(0)\n\ts_barrier" ::: "memory")
; template <int DQK>
; __device__ __forceinline__ void attn_pass4(LAS unsigned char* lds, const bf16* Qp, int qpitch, const bf16* Kp, int kpitch, const bf16* Vp, int vpitch, int q0, f32x16 (&o)[4], float (&rl)[16]) {
;     ...
;     { const bf16* qrow = Qp + (size_t)(q0 + wid * 32 + r32) * qpitch + 8 * hi;
; #pragma unroll
;       for (int d0 = 0; d0 < DQK / 16; ++d0) qf[d0] = *(const bf16x8*)(qrow + 16 * d0); }
;     const int NT = (q0 + 256) / 64;
;     const int qw0 = q0 + wid * 32;
;     const unsigned lds0 = (unsigned)(size_t)lds;
;     constexpr int KS = G::KP / 16, KD = DQK / 8, KJ = (KS + 7) / 8, VS = VP / 16, VD = 16, VJ = (VS + 7) / 8;
;     unsigned koff[KJ], voff[VJ];
; #pragma unroll
;     for (int j = 0; j < KJ; ++j) { const int sidx = (j * 8 + wid) * 64 + lane, row = (sidx / KS) & 63, c = sidx % KS; koff[j] = (unsigned)(row * kpitch + (c < KD ? c : KD - 1) * 8) * 2u; }
; #pragma unroll
;     for (int j = 0; j < VJ; ++j) { const int sidx = (j * 8 + wid) * 64 + lane, row = (sidx / VS) & 63, c = sidx % VS; voff[j] = (unsigned)(row * vpitch + (c < VD ? c : VD - 1) * 8) * 2u; }
;     ...
;     ATT_DMA(0, 0, 0); ATT_BAR();
.LBB0_609:
	v_mov_b32_e32 v32, v242
	s_and_b64 s[2:3], s[14:15], exec
	s_cselect_b32 s30, s37, s36
	v_readfirstlane_b32 s5, v32
	s_ashr_i32 s3, s5, 6
	s_lshl_b32 s76, s3, 5
	v_and_b32_e32 v34, 31, v32
	s_add_i32 s76, s76, s30
	v_or_b32_e32 v166, s76, v34
	v_ashrrev_i32_e32 v167, 31, v166
	v_bfe_u32 v180, v32, 5, 1
	v_lshlrev_b64 v[36:37], 11, v[166:167]
	v_lshl_add_u64 v[36:37], s[50:51], 0, v[36:37]
	v_lshlrev_b32_e32 v168, 4, v180
	v_mov_b32_e32 v169, v33
	v_lshl_add_u64 v[36:37], v[36:37], 0, v[168:169]
	global_load_dwordx4 v[146:149], v[36:37], off
	global_load_dwordx4 v[150:153], v[36:37], off offset:32
	global_load_dwordx4 v[154:157], v[36:37], off offset:64
	global_load_dwordx4 v[158:161], v[36:37], off offset:96
	v_mov_b32_e32 v35, s5
	v_bfi_b32 v35, s79, v35, v32
	v_mul_hi_i32 v36, v35, s85
	v_lshrrev_b32_e32 v37, 31, v36
	v_ashrrev_i32_e32 v36, 1, v36
	v_add_u32_e32 v36, v36, v37
	v_lshl_add_u32 v37, v36, 3, v36
	v_sub_u32_e32 v37, v35, v37
	v_lshlrev_b32_e32 v36, 11, v36
	v_and_b32_e32 v36, 0x1f800, v36
	v_min_i32_e32 v37, 7, v37
	s_cmp_lt_i32 s3, 9
	s_cselect_b64 s[64:65], -1, 0
	s_cmp_gt_i32 s3, 8
	v_lshl_add_u32 v170, v37, 4, v36
	s_cbranch_scc1 .LBB0_611
	v_mov_b32_e32 v171, v33
	s_lshl_b32 s2, s3, 10
	v_lshl_add_u64 v[36:37], s[52:53], 0, v[170:171]
	s_mov_b32 m0, s2
	s_nop 0
	global_load_lds_dwordx4 v[36:37], off
.LBB0_611:
	v_add_u32_e32 v36, 0x200, v35
	v_mul_hi_i32 v37, v36, s85
	v_lshrrev_b32_e32 v38, 31, v37
	v_ashrrev_i32_e32 v37, 1, v37
	v_add_u32_e32 v37, v37, v38
	v_lshl_add_u32 v38, v37, 3, v37
	v_sub_u32_e32 v38, v36, v38
	v_lshlrev_b32_e32 v37, 11, v37
	s_add_i32 s2, s3, 8
	v_and_b32_e32 v37, 0x1f800, v37
	v_min_i32_e32 v38, 7, v38
	s_cmp_lt_i32 s3, 1
	s_cselect_b64 s[10:11], -1, 0
	s_cmp_gt_i32 s3, 0
	v_lshl_add_u32 v176, v38, 4, v37
	s_cbranch_scc1 .LBB0_613
	v_mov_b32_e32 v177, v33
	s_lshl_b32 s8, s2, 10
	v_lshl_add_u64 v[38:39], s[52:53], 0, v[176:177]
	s_mov_b32 m0, s8
	s_nop 0
	global_load_lds_dwordx4 v[38:39], off
.LBB0_613:
	v_mul_hi_i32 v37, v35, s4
	v_lshrrev_b32_e32 v38, 31, v37
	v_ashrrev_i32_e32 v37, 3, v37
	v_add_u32_e32 v37, v37, v38
	v_mul_lo_u32 v38, v37, 20
	v_sub_u32_e32 v38, v35, v38
	v_lshlrev_b32_e32 v37, 11, v37
	s_cmp_lt_i32 s3, 20
	v_and_b32_e32 v37, 0x1f800, v37
	v_min_i32_e32 v38, 15, v38
	s_cselect_b64 s[66:67], -1, 0
	v_lshl_add_u32 v172, v38, 4, v37
	s_and_b64 vcc, exec, s[66:67]
	s_cbranch_vccz .LBB0_615
	s_lshl_b32 s8, s3, 10
	v_mov_b32_e32 v173, v33
	s_add_i32 s8, s8, 0
	v_lshl_add_u64 v[38:39], s[54:55], 0, v[172:173]
	s_addk_i32 s8, 0x4800
	s_mov_b32 m0, s8
	s_nop 0
	global_load_lds_dwordx4 v[38:39], off
.LBB0_615:
	v_mul_hi_i32 v37, v36, s4
	v_lshrrev_b32_e32 v38, 31, v37
	v_ashrrev_i32_e32 v37, 3, v37
	v_add_u32_e32 v37, v37, v38
	v_mul_lo_u32 v38, v37, 20
	v_sub_u32_e32 v36, v36, v38
	v_lshlrev_b32_e32 v37, 11, v37
	v_and_b32_e32 v37, 0x1f800, v37
	v_min_i32_e32 v36, 15, v36
	s_cmp_lt_i32 s3, 12
	s_cselect_b64 s[68:69], -1, 0
	s_cmp_gt_i32 s3, 11
	v_lshl_add_u32 v174, v36, 4, v37
	s_cbranch_scc1 .LBB0_617
	s_lshl_b32 s8, s2, 10
	v_mov_b32_e32 v175, v33
	s_add_i32 s8, s8, 0
	v_lshl_add_u64 v[36:37], s[54:55], 0, v[174:175]
	s_addk_i32 s8, 0x4800
	s_mov_b32 m0, s8
	s_nop 0
	global_load_lds_dwordx4 v[36:37], off
.LBB0_617:
	v_add_u32_e32 v35, 0x400, v35
	v_mul_hi_i32 v36, v35, s4
	v_lshrrev_b32_e32 v37, 31, v36
	v_ashrrev_i32_e32 v36, 3, v36
	v_add_u32_e32 v36, v36, v37
	v_mul_lo_u32 v37, v36, 20
	v_sub_u32_e32 v35, v35, v37
	v_lshlrev_b32_e32 v36, 11, v36
	v_and_b32_e32 v36, 0x1f800, v36
	v_min_i32_e32 v35, 15, v35
	s_cmp_gt_i32 s3, 3
	v_lshl_add_u32 v178, v35, 4, v36
	s_cbranch_scc1 .LBB0_619
	s_lshl_b32 s8, s3, 10
	v_mov_b32_e32 v179, v33
	s_add_i32 s8, s8, 0
	v_lshl_add_u64 v[36:37], s[54:55], 0, v[178:179]
	s_add_i32 s8, s8, 0x8800
	s_mov_b32 m0, s8
	s_nop 0
	global_load_lds_dwordx4 v[36:37], off

; template <int DQK>
; __device__ __forceinline__ void attn_pass4(LAS unsigned char* lds, const bf16* Qp, int qpitch, const bf16* Kp, int kpitch, const bf16* Vp, int vpitch, int q0, f32x16 (&o)[4], float (&rl)[16]) {
;     ...
;         for (int t = 0; t < NT; ++t) {
;             const int vnext = ATT_VNEXT(vcur);
;             if (t + 1 < NT) ATT_DMA(t + 1, (t + 1) & 1, vnext);
.LBB0_621:
	s_add_i32 s25, s24, 1
	s_cmp_lg_u32 s24, 2
	s_cselect_b32 s35, s25, 0
	s_add_i32 s25, s72, 1
	s_cmp_ge_u32 s25, s31
	s_cbranch_scc1 .LBB0_625
	s_bitcmp1_b32 s25, 0
	s_cselect_b32 s73, 0x2400, 0
	s_add_i32 s74, s73, s5

	s_mov_b32 m0, s74
	s_nop 0
	global_load_lds_dwordx4 v170, s[70:71]
	s_andn2_b64 vcc, exec, s[10:11]
	s_cbranch_vccnz .LBB0_624
	s_add_i32 s73, s73, s80

	s_mov_b32 m0, s73
	s_nop 0
	global_load_lds_dwordx4 v176, s[70:71]
.LBB0_624:
	s_add_u32 s74, s70, 0x4000000
	s_mul_i32 s73, s35, 0x5000
	s_addc_u32 s75, s71, 0
	s_add_i32 s73, s26, s73

	s_mov_b32 m0, s73
	s_nop 0
	global_load_lds_dwordx4 v172, s[74:75]
	s_add_i32 vcc_lo, s73, 0x2000

	s_mov_b32 m0, vcc_lo
	s_nop 0
	global_load_lds_dwordx4 v174, s[74:75]
	v_readfirstlane_b32 s32, v242
	s_cmpk_gt_u32 s32, 0xff
	s_cbranch_scc1 .Lskip_v2_0
	v_lshl_add_u64 v[114:115], s[74:75], 0, v[178:179]
	s_addk_i32 s73, 0x4000
	s_mov_b32 m0, s73
	s_nop 0
	global_load_lds_dwordx4 v[114:115], off

; template <int DQK>
; __device__ __forceinline__ void attn_pass4(LAS unsigned char* lds, const bf16* Qp, int qpitch, const bf16* Kp, int kpitch, const bf16* Vp, int vpitch, int q0, f32x16 (&o)[4], float (&rl)[16]) {
;     ...
;         for (int t = 0; t < NT; ++t) {
;             const int vnext = ATT_VNEXT(vcur);
;             if (t + 1 < NT) ATT_DMA(t + 1, (t + 1) & 1, vnext);
.LBB0_644:
	s_add_i32 s10, s26, 1
	s_cmp_lg_u32 s26, 2
	s_mov_b32 s5, s26
	s_cselect_b32 s26, s10, 0
	s_add_i32 s27, s18, 1
	s_cmp_ge_u32 s27, s31
	s_cbranch_scc1 .LBB0_651
	s_andn2_b64 vcc, exec, s[64:65]
	s_cbranch_vccnz .LBB0_647
	s_bitcmp1_b32 s27, 0
	s_cselect_b32 s10, 0x2400, 0
	s_add_i32 s10, s10, s75
	v_lshl_add_u64 v[130:131], s[70:71], 0, v[170:171]
	s_mov_b32 m0, s10
	s_nop 0
	global_load_lds_dwordx4 v[130:131], off
.LBB0_647:
	s_add_u32 s10, s70, 0x4000000
	s_mul_i32 s25, s26, 0x5000
	s_addc_u32 s11, s71, 0
	s_andn2_b64 vcc, exec, s[66:67]
	s_addk_i32 s25, 0x4800
	s_cbranch_vccnz .LBB0_649
	s_add_i32 s35, s25, s75
	v_lshl_add_u64 v[130:131], s[10:11], 0, v[172:173]
	s_mov_b32 m0, s35
	s_nop 0
	global_load_lds_dwordx4 v[130:131], off
.LBB0_649:
	s_andn2_b64 vcc, exec, s[68:69]
	s_cbranch_vccnz .LBB0_651
	s_add_i32 s25, s25, s80
	v_lshl_add_u64 v[130:131], s[10:11], 0, v[174:175]
	s_mov_b32 m0, s25
	s_nop 0
	global_load_lds_dwordx4 v[130:131], off

; __device__ __forceinline__ int crow(int r, int hi) { return (r & 3) + 8 * (r >> 2) + 4 * hi; }
; template <int DQK>
; __device__ __forceinline__ void attn_pass4(LAS unsigned char* lds, const bf16* Qp, int qpitch, const bf16* Kp, int kpitch, const bf16* Vp, int vpitch, int q0, f32x16 (&o)[4], float (&rl)[16]) {
;     ...
;     for (int r = 0; r < 16; ++r) rl[r] = 1.0f / wsf[32 + crow(r, hi)];
; __global__ void __launch_bounds__(NWAVES * 64, 2) fwd_kernel(Args args) {
;     ...
;                     for (int r4 = 0; r4 < 4; ++r4) scrO[db * 4 + r4] = (f32x4){o[db][4 * r4] * rl[4 * r4], o[db][4 * r4 + 1] * rl[4 * r4 + 1], o[db][4 * r4 + 2] * rl[4 * r4 + 2], o[db][4 * r4 + 3] * rl[4 * r4 + 3]};
.LBB0_809:
	s_waitcnt lgkmcnt(0)
	v_div_scale_f32 v32, s[2:3], v111, v111, 1.0
	v_rcp_f32_e32 v114, v32
	s_barrier
	v_fma_f32 v115, -v32, v114, 1.0
	v_fmac_f32_e32 v114, v115, v114
	v_div_scale_f32 v115, vcc, 1.0, v111, 1.0
	v_mul_f32_e32 v116, v115, v114
	v_fma_f32 v117, -v32, v116, v115
	v_fmac_f32_e32 v116, v117, v114
	v_fma_f32 v32, -v32, v116, v115
	v_div_fmas_f32 v32, v32, v114, v116
	v_div_fixup_f32 v111, v32, v111, 1.0
	v_div_scale_f32 v32, s[2:3], v110, v110, 1.0
	v_rcp_f32_e32 v114, v32
	v_mov_b32_e32 v169, v33
	v_fma_f32 v115, -v32, v114, 1.0
	v_fmac_f32_e32 v114, v115, v114
	v_div_scale_f32 v115, vcc, 1.0, v110, 1.0
	v_mul_f32_e32 v116, v115, v114
	v_fma_f32 v117, -v32, v116, v115
	v_fmac_f32_e32 v116, v117, v114
	v_fma_f32 v32, -v32, v116, v115
	v_div_fmas_f32 v32, v32, v114, v116
	v_div_fixup_f32 v110, v32, v110, 1.0
	v_div_scale_f32 v32, s[2:3], v113, v113, 1.0
	v_rcp_f32_e32 v114, v32
	v_pk_mul_f32 v[82:83], v[82:83], v[110:111]
	v_pk_mul_f32 v[66:67], v[66:67], v[110:111]
	v_pk_mul_f32 v[50:51], v[50:51], v[110:111]
	v_fma_f32 v115, -v32, v114, 1.0
	v_fmac_f32_e32 v114, v115, v114
	v_div_scale_f32 v115, vcc, 1.0, v113, 1.0
	v_mul_f32_e32 v116, v115, v114
	v_fma_f32 v117, -v32, v116, v115
	v_fmac_f32_e32 v116, v117, v114
	v_fma_f32 v32, -v32, v116, v115
	v_div_fmas_f32 v32, v32, v114, v116
	v_div_fixup_f32 v113, v32, v113, 1.0
	v_div_scale_f32 v32, s[2:3], v112, v112, 1.0
	v_rcp_f32_e32 v114, v32
	v_pk_mul_f32 v[34:35], v[34:35], v[110:111]
	v_fma_f32 v115, -v32, v114, 1.0
	v_fmac_f32_e32 v114, v115, v114
	v_div_scale_f32 v115, vcc, 1.0, v112, 1.0
	v_mul_f32_e32 v116, v115, v114
	v_fma_f32 v117, -v32, v116, v115
	v_fmac_f32_e32 v116, v117, v114
	v_fma_f32 v32, -v32, v116, v115
	v_div_fmas_f32 v32, v32, v114, v116
	v_div_fixup_f32 v112, v32, v112, 1.0
	v_div_scale_f32 v32, s[2:3], v107, v107, 1.0
	v_rcp_f32_e32 v114, v32
	v_pk_mul_f32 v[84:85], v[84:85], v[112:113]
	v_pk_mul_f32 v[68:69], v[68:69], v[112:113]
	v_pk_mul_f32 v[52:53], v[52:53], v[112:113]
	v_fma_f32 v115, -v32, v114, 1.0
	v_fmac_f32_e32 v114, v115, v114
	v_div_scale_f32 v115, vcc, 1.0, v107, 1.0
	v_mul_f32_e32 v116, v115, v114
	v_fma_f32 v117, -v32, v116, v115
	v_fmac_f32_e32 v116, v117, v114
	v_fma_f32 v32, -v32, v116, v115
	v_div_fmas_f32 v32, v32, v114, v116
	v_div_fixup_f32 v107, v32, v107, 1.0
	v_div_scale_f32 v32, s[2:3], v106, v106, 1.0
	v_rcp_f32_e32 v114, v32
	v_pk_mul_f32 v[36:37], v[36:37], v[112:113]
	v_fma_f32 v115, -v32, v114, 1.0
	v_fmac_f32_e32 v114, v115, v114
	v_div_scale_f32 v115, vcc, 1.0, v106, 1.0
	v_mul_f32_e32 v116, v115, v114
	v_fma_f32 v117, -v32, v116, v115
	v_fmac_f32_e32 v116, v117, v114
	v_fma_f32 v32, -v32, v116, v115
	v_div_fmas_f32 v32, v32, v114, v116
	v_div_fixup_f32 v106, v32, v106, 1.0
	v_div_scale_f32 v32, s[2:3], v109, v109, 1.0
	v_rcp_f32_e32 v114, v32
	s_nop 0
	v_fma_f32 v115, -v32, v114, 1.0
	v_fmac_f32_e32 v114, v115, v114
	v_div_scale_f32 v115, vcc, 1.0, v109, 1.0
	v_mul_f32_e32 v116, v115, v114
	v_fma_f32 v117, -v32, v116, v115
	v_fmac_f32_e32 v116, v117, v114
	v_fma_f32 v32, -v32, v116, v115
	v_div_fmas_f32 v32, v32, v114, v116
	v_div_fixup_f32 v109, v32, v109, 1.0
	v_div_scale_f32 v32, s[2:3], v108, v108, 1.0
	v_rcp_f32_e32 v114, v32
	s_nop 0
	v_fma_f32 v115, -v32, v114, 1.0
	v_fmac_f32_e32 v114, v115, v114
	v_div_scale_f32 v115, vcc, 1.0, v108, 1.0
	v_mul_f32_e32 v116, v115, v114
	v_fma_f32 v117, -v32, v116, v115
	v_fmac_f32_e32 v116, v117, v114
	v_fma_f32 v32, -v32, v116, v115
	v_div_fmas_f32 v32, v32, v114, v116
	v_div_fixup_f32 v108, v32, v108, 1.0
	v_div_scale_f32 v32, s[2:3], v103, v103, 1.0
	v_rcp_f32_e32 v114, v32
	s_nop 0
	v_fma_f32 v115, -v32, v114, 1.0
	v_fmac_f32_e32 v114, v115, v114
	v_div_scale_f32 v115, vcc, 1.0, v103, 1.0
	v_mul_f32_e32 v116, v115, v114
	v_fma_f32 v117, -v32, v116, v115
	v_fmac_f32_e32 v116, v117, v114
	v_fma_f32 v32, -v32, v116, v115
	v_div_fmas_f32 v32, v32, v114, v116
	v_div_fixup_f32 v103, v32, v103, 1.0
	v_div_scale_f32 v32, s[2:3], v102, v102, 1.0
	v_rcp_f32_e32 v114, v32
	s_nop 0
	v_fma_f32 v115, -v32, v114, 1.0
	v_fmac_f32_e32 v114, v115, v114
	v_div_scale_f32 v115, vcc, 1.0, v102, 1.0
	v_mul_f32_e32 v116, v115, v114
	v_fma_f32 v117, -v32, v116, v115
	v_fmac_f32_e32 v116, v117, v114
	v_fma_f32 v32, -v32, v116, v115
	v_div_fmas_f32 v32, v32, v114, v116
	v_div_fixup_f32 v102, v32, v102, 1.0
	v_div_scale_f32 v32, s[2:3], v105, v105, 1.0
	v_rcp_f32_e32 v114, v32
	s_nop 0
	v_fma_f32 v115, -v32, v114, 1.0
	v_fmac_f32_e32 v114, v115, v114
	v_div_scale_f32 v115, vcc, 1.0, v105, 1.0
	v_mul_f32_e32 v116, v115, v114
	v_fma_f32 v117, -v32, v116, v115
	v_fmac_f32_e32 v116, v117, v114
	v_fma_f32 v32, -v32, v116, v115
	v_div_fmas_f32 v32, v32, v114, v116
	v_div_fixup_f32 v105, v32, v105, 1.0
	v_div_scale_f32 v32, s[2:3], v104, v104, 1.0
	v_rcp_f32_e32 v114, v32
	s_nop 0
	v_fma_f32 v115, -v32, v114, 1.0
	v_fmac_f32_e32 v114, v115, v114
	v_div_scale_f32 v115, vcc, 1.0, v104, 1.0
	v_mul_f32_e32 v116, v115, v114
	v_fma_f32 v117, -v32, v116, v115
	v_fmac_f32_e32 v116, v117, v114
	v_fma_f32 v32, -v32, v116, v115
	v_div_fmas_f32 v32, v32, v114, v116
	v_div_fixup_f32 v104, v32, v104, 1.0
	v_div_scale_f32 v32, s[2:3], v99, v99, 1.0
	v_rcp_f32_e32 v114, v32
	s_nop 0
	v_fma_f32 v115, -v32, v114, 1.0
	v_fmac_f32_e32 v114, v115, v114
	v_div_scale_f32 v115, vcc, 1.0, v99, 1.0
	v_mul_f32_e32 v116, v115, v114
	v_fma_f32 v117, -v32, v116, v115
	v_fmac_f32_e32 v116, v117, v114
	v_fma_f32 v32, -v32, v116, v115
	v_div_fmas_f32 v32, v32, v114, v116
	v_div_fixup_f32 v99, v32, v99, 1.0
	v_div_scale_f32 v32, s[2:3], v98, v98, 1.0
	v_rcp_f32_e32 v114, v32
	s_nop 0
	v_fma_f32 v115, -v32, v114, 1.0
; template <int DQK>
; __device__ __forceinline__ void attn_pass4(LAS unsigned char* lds, const bf16* Qp, int qpitch, const bf16* Kp, int kpitch, const bf16* Vp, int vpitch, int q0, f32x16 (&o)[4], float (&rl)[16]) {
;     ...
;     { const bf16* qrow = Qp + (size_t)(q0 + wid * 32 + r32) * qpitch + 8 * hi;
; #pragma unroll
;       for (int d0 = 0; d0 < DQK / 16; ++d0) qf[d0] = *(const bf16x8*)(qrow + 16 * d0); }
;     const int NT = (q0 + 256) / 64;
;     const int qw0 = q0 + wid * 32;
;     const unsigned lds0 = (unsigned)(size_t)lds;
;     constexpr int KS = G::KP / 16, KD = DQK / 8, KJ = (KS + 7) / 8, VS = VP / 16, VD = 16, VJ = (VS + 7) / 8;
;     unsigned koff[KJ], voff[VJ];
; #pragma unroll
;     for (int j = 0; j < KJ; ++j) { const int sidx = (j * 8 + wid) * 64 + lane, row = (sidx / KS) & 63, c = sidx % KS; koff[j] = (unsigned)(row * kpitch + (c < KD ? c : KD - 1) * 8) * 2u; }
; #pragma unroll
;     for (int j = 0; j < VJ; ++j) { const int sidx = (j * 8 + wid) * 64 + lane, row = (sidx / VS) & 63, c = sidx % VS; voff[j] = (unsigned)(row * vpitch + (c < VD ? c : VD - 1) * 8) * 2u; }
; __global__ void __launch_bounds__(NWAVES * 64, 2) fwd_kernel(Args args) {
;     ...
;                 int t1 = threadIdx.x; asm volatile("" : "+v"(t1));
;                 f32x4* scrO = (f32x4*)((float*)(ws + WS_O0) + ((size_t)bx * 512 + t1) * 64);
; #pragma unroll
;                 for (int db = 0; db < 4; ++db)
; #pragma unroll
;                     for (int r4 = 0; r4 < 4; ++r4) scrO[db * 4 + r4] = (f32x4){o[db][4 * r4] * rl[4 * r4], o[db][4 * r4 + 1] * rl[4 * r4 + 1], o[db][4 * r4 + 2] * rl[4 * r4 + 2], o[db][4 * r4 + 3] * rl[4 * r4 + 3]};
	v_fmac_f32_e32 v114, v115, v114
	v_div_scale_f32 v115, vcc, 1.0, v98, 1.0
	v_mul_f32_e32 v116, v115, v114
	v_fma_f32 v117, -v32, v116, v115
	v_fmac_f32_e32 v116, v117, v114
	v_fma_f32 v32, -v32, v116, v115
	v_div_fmas_f32 v32, v32, v114, v116
	v_div_fixup_f32 v98, v32, v98, 1.0
	v_div_scale_f32 v32, s[2:3], v101, v101, 1.0
	v_rcp_f32_e32 v114, v32
	s_nop 0
	v_fma_f32 v115, -v32, v114, 1.0
	v_fmac_f32_e32 v114, v115, v114
	v_div_scale_f32 v115, vcc, 1.0, v101, 1.0
	v_mul_f32_e32 v116, v115, v114
	v_fma_f32 v117, -v32, v116, v115
	v_fmac_f32_e32 v116, v117, v114
	v_fma_f32 v32, -v32, v116, v115
	v_div_fmas_f32 v32, v32, v114, v116
	v_div_fixup_f32 v101, v32, v101, 1.0
	v_div_scale_f32 v32, s[2:3], v100, v100, 1.0
	v_rcp_f32_e32 v114, v32
	s_nop 0
	v_fma_f32 v115, -v32, v114, 1.0
	v_fmac_f32_e32 v114, v115, v114
	v_div_scale_f32 v115, vcc, 1.0, v100, 1.0
	v_mul_f32_e32 v116, v115, v114
	v_fma_f32 v117, -v32, v116, v115
	v_fmac_f32_e32 v116, v117, v114
	v_fma_f32 v32, -v32, v116, v115
	v_div_fmas_f32 v32, v32, v114, v116
	v_mov_b32_e32 v114, v242
	v_div_fixup_f32 v100, v32, v100, 1.0
	v_ashrrev_i32_e32 v115, 31, v114
	v_lshl_add_u64 v[114:115], s[42:43], 0, v[114:115]
	v_lshlrev_b64 v[114:115], 8, v[114:115]
	v_lshl_add_u64 v[114:115], s[28:29], 0, v[114:115]
	global_store_dwordx4 v[114:115], v[82:85], off
	global_store_dwordx4 v[114:115], v[66:69], off offset:64
	global_store_dwordx4 v[114:115], v[50:53], off offset:128
	v_pk_mul_f32 v[82:83], v[86:87], v[106:107]
	v_pk_mul_f32 v[84:85], v[88:89], v[108:109]
	v_pk_mul_f32 v[66:67], v[70:71], v[106:107]
	v_pk_mul_f32 v[68:69], v[72:73], v[108:109]
	v_pk_mul_f32 v[50:51], v[54:55], v[106:107]
	v_pk_mul_f32 v[52:53], v[56:57], v[108:109]
	global_store_dwordx4 v[114:115], v[34:37], off offset:192
	global_store_dwordx4 v[114:115], v[82:85], off offset:16
	global_store_dwordx4 v[114:115], v[66:69], off offset:80
	v_pk_mul_f32 v[34:35], v[38:39], v[106:107]
	v_pk_mul_f32 v[36:37], v[40:41], v[108:109]
	v_pk_mul_f32 v[82:83], v[90:91], v[102:103]
	v_pk_mul_f32 v[84:85], v[92:93], v[104:105]
	v_pk_mul_f32 v[66:67], v[74:75], v[102:103]
	v_pk_mul_f32 v[68:69], v[76:77], v[104:105]
	global_store_dwordx4 v[114:115], v[50:53], off offset:144
	global_store_dwordx4 v[114:115], v[34:37], off offset:208
	global_store_dwordx4 v[114:115], v[82:85], off offset:32
	v_pk_mul_f32 v[50:51], v[58:59], v[102:103]
	v_pk_mul_f32 v[52:53], v[60:61], v[104:105]
	v_pk_mul_f32 v[34:35], v[42:43], v[102:103]
	v_pk_mul_f32 v[36:37], v[44:45], v[104:105]
	v_pk_mul_f32 v[82:83], v[94:95], v[98:99]
	v_pk_mul_f32 v[84:85], v[96:97], v[100:101]
	global_store_dwordx4 v[114:115], v[66:69], off offset:96
	global_store_dwordx4 v[114:115], v[50:53], off offset:160
	global_store_dwordx4 v[114:115], v[34:37], off offset:224
	v_pk_mul_f32 v[66:67], v[78:79], v[98:99]
	v_pk_mul_f32 v[68:69], v[80:81], v[100:101]
	v_pk_mul_f32 v[50:51], v[62:63], v[98:99]
	v_pk_mul_f32 v[52:53], v[64:65], v[100:101]
	v_pk_mul_f32 v[34:35], v[46:47], v[98:99]
	v_pk_mul_f32 v[36:37], v[48:49], v[100:101]
	v_mov_b32_e32 v32, v242
	global_store_dwordx4 v[114:115], v[82:85], off offset:48
	global_store_dwordx4 v[114:115], v[66:69], off offset:112
	global_store_dwordx4 v[114:115], v[50:53], off offset:176
	global_store_dwordx4 v[114:115], v[34:37], off offset:240
	s_nop 0
	v_readfirstlane_b32 s3, v32
	s_ashr_i32 s80, s3, 6
	s_lshl_b32 s76, s80, 5
	v_and_b32_e32 v34, 31, v32
	s_add_i32 s76, s76, s30
	v_or_b32_e32 v166, s76, v34
	v_ashrrev_i32_e32 v167, 31, v166
	v_bfe_u32 v180, v32, 5, 1
	v_lshlrev_b64 v[36:37], 11, v[166:167]
	v_lshl_add_u64 v[36:37], s[50:51], 0, v[36:37]
	v_lshlrev_b32_e32 v168, 4, v180
	v_lshl_add_u64 v[36:37], v[36:37], 0, v[168:169]
	global_load_dwordx4 v[146:149], v[36:37], off offset:128
	global_load_dwordx4 v[150:153], v[36:37], off offset:160
	global_load_dwordx4 v[154:157], v[36:37], off offset:192
	global_load_dwordx4 v[158:161], v[36:37], off offset:224
	v_mov_b32_e32 v35, s3
	v_bfi_b32 v35, s79, v35, v32
	v_mul_hi_i32 v36, v35, s85
	v_lshrrev_b32_e32 v37, 31, v36
	v_ashrrev_i32_e32 v36, 1, v36
	v_add_u32_e32 v36, v36, v37
	v_lshl_add_u32 v37, v36, 3, v36
	v_sub_u32_e32 v37, v35, v37
	v_lshlrev_b32_e32 v36, 11, v36
	v_and_b32_e32 v36, 0x1f800, v36
	v_min_i32_e32 v37, 7, v37
	s_cmp_lt_i32 s80, 9
	v_lshl_add_u32 v170, v37, 4, v36
	s_cselect_b64 s[14:15], -1, 0
	s_cmp_gt_i32 s80, 8
	s_cbranch_scc1 .LBB0_811
	v_mov_b32_e32 v171, v33
	s_lshl_b32 s2, s80, 10
	v_lshl_add_u64 v[36:37], s[56:57], 0, v[170:171]
	s_mov_b32 m0, s2
	s_nop 0
	global_load_lds_dwordx4 v[36:37], off
.LBB0_811:
	v_add_u32_e32 v36, 0x200, v35
	v_mul_hi_i32 v37, v36, s85
	v_lshrrev_b32_e32 v38, 31, v37
	v_ashrrev_i32_e32 v37, 1, v37
	v_add_u32_e32 v37, v37, v38
	v_lshl_add_u32 v38, v37, 3, v37
	v_sub_u32_e32 v38, v36, v38
	v_lshlrev_b32_e32 v37, 11, v37
	s_add_i32 s2, s80, 8
	v_and_b32_e32 v37, 0x1f800, v37
	v_min_i32_e32 v38, 7, v38
	s_cmp_lt_i32 s80, 1
	s_cselect_b64 s[10:11], -1, 0
	s_cmp_gt_i32 s80, 0
	v_lshl_add_u32 v176, v38, 4, v37
	s_cbranch_scc1 .LBB0_813
	v_mov_b32_e32 v177, v33
	s_lshl_b32 s5, s2, 10
	v_lshl_add_u64 v[38:39], s[56:57], 0, v[176:177]
	s_mov_b32 m0, s5
	s_nop 0
	global_load_lds_dwordx4 v[38:39], off
.LBB0_813:
	v_mul_hi_i32 v37, v35, s4
	v_lshrrev_b32_e32 v38, 31, v37
	v_ashrrev_i32_e32 v37, 3, v37
	v_add_u32_e32 v37, v37, v38
	v_mul_lo_u32 v38, v37, 20
	v_sub_u32_e32 v38, v35, v38
	v_lshlrev_b32_e32 v37, 11, v37
	s_cmp_lt_i32 s80, 20
	v_and_b32_e32 v37, 0x1f800, v37
	v_min_i32_e32 v38, 15, v38
	s_cselect_b64 s[66:67], -1, 0
	v_lshl_add_u32 v172, v38, 4, v37
	s_and_b64 vcc, exec, s[66:67]
	s_cbranch_vccz .LBB0_815
	s_lshl_b32 s5, s80, 10
	v_mov_b32_e32 v173, v33
	s_add_i32 s5, s5, 0
	v_lshl_add_u64 v[38:39], s[54:55], 0, v[172:173]
	s_addk_i32 s5, 0x4800
	s_mov_b32 m0, s5
	s_nop 0
	global_load_lds_dwordx4 v[38:39], off
.LBB0_815:
	v_mul_hi_i32 v37, v36, s4
	v_lshrrev_b32_e32 v38, 31, v37
	v_ashrrev_i32_e32 v37, 3, v37
	v_add_u32_e32 v37, v37, v38
	v_mul_lo_u32 v38, v37, 20
	v_sub_u32_e32 v36, v36, v38
	v_lshlrev_b32_e32 v37, 11, v37
	v_and_b32_e32 v37, 0x1f800, v37
	v_min_i32_e32 v36, 15, v36
	s_cmp_lt_i32 s80, 12
	s_cselect_b64 s[68:69], -1, 0
	s_cmp_gt_i32 s80, 11
	v_lshl_add_u32 v174, v36, 4, v37
	s_cbranch_scc1 .LBB0_817
	s_lshl_b32 s5, s2, 10
	v_mov_b32_e32 v175, v33
	s_add_i32 s5, s5, 0
	v_lshl_add_u64 v[36:37], s[54:55], 0, v[174:175]
	s_addk_i32 s5, 0x4800
	s_mov_b32 m0, s5
	s_nop 0
	global_load_lds_dwordx4 v[36:37], off
.LBB0_817:
	v_add_u32_e32 v35, 0x400, v35
	v_mul_hi_i32 v36, v35, s4
	v_lshrrev_b32_e32 v37, 31, v36
	v_ashrrev_i32_e32 v36, 3, v36
	v_add_u32_e32 v36, v36, v37
	v_mul_lo_u32 v37, v36, 20
	v_sub_u32_e32 v35, v35, v37
	v_lshlrev_b32_e32 v36, 11, v36
	v_and_b32_e32 v36, 0x1f800, v36
	v_min_i32_e32 v35, 15, v35
	s_cmp_gt_i32 s80, 3
	v_lshl_add_u32 v178, v35, 4, v36
	s_cbranch_scc1 .LBB0_819
	s_lshl_b32 s5, s80, 10
	v_mov_b32_e32 v179, v33
	s_add_i32 s5, s5, 0
	v_lshl_add_u64 v[36:37], s[54:55], 0, v[178:179]
	s_add_i32 s5, s5, 0x8800
	s_mov_b32 m0, s5
	s_nop 0
	global_load_lds_dwordx4 v[36:37], off

; template <int DQK>
; __device__ __forceinline__ void attn_pass4(LAS unsigned char* lds, const bf16* Qp, int qpitch, const bf16* Kp, int kpitch, const bf16* Vp, int vpitch, int q0, f32x16 (&o)[4], float (&rl)[16]) {
;     ...
;         for (int t = 0; t < NT; ++t) {
;             const int vnext = ATT_VNEXT(vcur);
;             if (t + 1 < NT) ATT_DMA(t + 1, (t + 1) & 1, vnext);
.LBB0_821:
	s_add_i32 s24, s35, 1
	s_cmp_lg_u32 s35, 2
	s_cselect_b32 s24, s24, 0
	s_add_i32 s25, s72, 1
	s_cmp_ge_u32 s25, s31
	s_cbranch_scc1 .LBB0_825
	s_bitcmp1_b32 s25, 0
	s_cselect_b32 s73, 0x2400, 0
	s_add_i32 s74, s73, s3

	s_mov_b32 m0, s74
	s_nop 0
	global_load_lds_dwordx4 v170, s[70:71]
	s_andn2_b64 vcc, exec, s[10:11]
	s_cbranch_vccnz .LBB0_824
	s_add_i32 s73, s73, s27

	s_mov_b32 m0, s73
	s_nop 0
	global_load_lds_dwordx4 v176, s[70:71]
.LBB0_824:
	s_add_u32 s74, s70, 0x3ffff80
	s_mul_i32 s73, s24, 0x5000
	s_addc_u32 s75, s71, 0
	s_add_i32 s73, s5, s73

	s_mov_b32 m0, s73
	s_nop 0
	global_load_lds_dwordx4 v172, s[74:75]
	s_add_i32 vcc_lo, s73, 0x2000

	s_mov_b32 m0, vcc_lo
	s_nop 0
	global_load_lds_dwordx4 v174, s[74:75]
	v_readfirstlane_b32 s32, v242
	s_cmpk_gt_u32 s32, 0xff
	s_cbranch_scc1 .Lskip_v2_1
	v_lshl_add_u64 v[114:115], s[74:75], 0, v[178:179]
	s_addk_i32 s73, 0x4000
	s_mov_b32 m0, s73
	s_nop 0
	global_load_lds_dwordx4 v[114:115], off

; template <int DQK>
; __device__ __forceinline__ void attn_pass4(LAS unsigned char* lds, const bf16* Qp, int qpitch, const bf16* Kp, int kpitch, const bf16* Vp, int vpitch, int q0, f32x16 (&o)[4], float (&rl)[16]) {
;     ...
;         for (int t = 0; t < NT; ++t) {
;             const int vnext = ATT_VNEXT(vcur);
;             if (t + 1 < NT) ATT_DMA(t + 1, (t + 1) & 1, vnext);
.LBB0_844:
	s_mov_b32 s26, s5
	s_add_i32 s5, s5, 1
	s_cmp_lg_u32 s26, 2
	s_cselect_b32 s5, s5, 0
	s_add_i32 s27, s18, 1
	s_cmp_ge_u32 s27, s31
	s_cbranch_scc1 .LBB0_851
	s_andn2_b64 vcc, exec, s[14:15]
	s_cbranch_vccnz .LBB0_847
	s_bitcmp1_b32 s27, 0
	s_cselect_b32 s10, 0x2400, 0
	s_add_i32 s10, s10, s74
	v_lshl_add_u64 v[130:131], s[70:71], 0, v[170:171]
	s_mov_b32 m0, s10
	s_nop 0
	global_load_lds_dwordx4 v[130:131], off
.LBB0_847:
	s_add_u32 s10, s70, 0x3ffff80
	s_mul_i32 s25, s5, 0x5000
	s_addc_u32 s11, s71, 0
	s_andn2_b64 vcc, exec, s[66:67]
	s_addk_i32 s25, 0x4800
	s_cbranch_vccnz .LBB0_849
	s_add_i32 s35, s25, s74
	v_lshl_add_u64 v[130:131], s[10:11], 0, v[172:173]
	s_mov_b32 m0, s35
	s_nop 0
	global_load_lds_dwordx4 v[130:131], off
.LBB0_849:
	s_andn2_b64 vcc, exec, s[68:69]
	s_cbranch_vccnz .LBB0_851
	s_add_i32 s25, s25, s75
	v_lshl_add_u64 v[130:131], s[10:11], 0, v[174:175]
	s_mov_b32 m0, s25
	s_nop 0
	global_load_lds_dwordx4 v[130:131], off

; template <int DQK>
; __device__ __forceinline__ void attn_pass4(LAS unsigned char* lds, const bf16* Qp, int qpitch, const bf16* Kp, int kpitch, const bf16* Vp, int vpitch, int q0, f32x16 (&o)[4], float (&rl)[16]) {
;     ...
;     { const bf16* qrow = Qp + (size_t)(q0 + wid * 32 + r32) * qpitch + 8 * hi;
; #pragma unroll
;       for (int d0 = 0; d0 < DQK / 16; ++d0) qf[d0] = *(const bf16x8*)(qrow + 16 * d0); }
;     const int NT = (q0 + 256) / 64;
;     const int qw0 = q0 + wid * 32;
;     const unsigned lds0 = (unsigned)(size_t)lds;
;     constexpr int KS = G::KP / 16, KD = DQK / 8, KJ = (KS + 7) / 8, VS = VP / 16, VD = 16, VJ = (VS + 7) / 8;
;     unsigned koff[KJ], voff[VJ];
; #pragma unroll
;     for (int j = 0; j < KJ; ++j) { const int sidx = (j * 8 + wid) * 64 + lane, row = (sidx / KS) & 63, c = sidx % KS; koff[j] = (unsigned)(row * kpitch + (c < KD ? c : KD - 1) * 8) * 2u; }
; #pragma unroll
;     for (int j = 0; j < VJ; ++j) { const int sidx = (j * 8 + wid) * 64 + lane, row = (sidx / VS) & 63, c = sidx % VS; voff[j] = (unsigned)(row * vpitch + (c < VD ? c : VD - 1) * 8) * 2u; }
.LBB0_2135:
	s_and_b64 s[2:3], s[44:45], exec
	v_mov_b32_e32 v0, v242
	s_cselect_b32 s66, s65, s64
	v_readfirstlane_b32 s2, v0
	s_ashr_i32 s67, s2, 6
	s_lshl_b32 s68, s67, 5
	v_and_b32_e32 v2, 31, v0
	s_add_i32 s68, s68, s66
	v_bfe_u32 v195, v0, 5, 1
	v_or_b32_e32 v197, s68, v2
	v_mad_i64_i32 v[4:5], s[10:11], v197, s19, v[176:177]
	v_lshlrev_b32_e32 v178, 4, v195
	v_mov_b32_e32 v179, v1
	v_lshl_add_u64 v[4:5], v[4:5], 0, v[178:179]
	global_load_dwordx4 v[128:131], v[4:5], off
	global_load_dwordx4 v[132:135], v[4:5], off offset:32
	global_load_dwordx4 v[136:139], v[4:5], off offset:64
	global_load_dwordx4 v[140:143], v[4:5], off offset:96
	global_load_dwordx4 v[144:147], v[4:5], off offset:128
	global_load_dwordx4 v[148:151], v[4:5], off offset:160
	global_load_dwordx4 v[152:155], v[4:5], off offset:192
	global_load_dwordx4 v[156:159], v[4:5], off offset:224
	global_load_dwordx4 v[160:163], v[4:5], off offset:256
	global_load_dwordx4 v[164:167], v[4:5], off offset:288
	global_load_dwordx4 v[168:171], v[4:5], off offset:320
	global_load_dwordx4 v[172:175], v[4:5], off offset:352
	v_mov_b32_e32 v3, s2
	v_bfi_b32 v3, s18, v3, v0
	v_mul_hi_i32 v4, v3, s26
	v_lshrrev_b32_e32 v5, 31, v4
	v_ashrrev_i32_e32 v4, 3, v4
	v_add_u32_e32 v4, v4, v5
	v_and_b32_e32 v5, 63, v4
	v_mul_lo_u32 v4, v4, 25
	v_sub_u32_e32 v4, v3, v4
	v_min_i32_e32 v4, 23, v4
	v_mul_u32_u24_e32 v5, 0xc00, v5
	s_cmp_lt_i32 s67, 25
	s_cselect_b64 s[46:47], -1, 0
	s_cmp_gt_i32 s67, 24
	v_lshl_add_u32 v180, v4, 4, v5
	s_cbranch_scc1 .LBB0_2137
	v_mov_b32_e32 v181, v1
	s_lshl_b32 s3, s67, 10
	v_lshl_add_u64 v[4:5], s[34:35], 0, v[180:181]
	s_mov_b32 m0, s3
	s_nop 0
	global_load_lds_dwordx4 v[4:5], off
.LBB0_2137:
	v_add_u32_e32 v4, 0x200, v3
	v_mul_hi_i32 v5, v4, s26
	v_lshrrev_b32_e32 v6, 31, v5
	v_ashrrev_i32_e32 v5, 3, v5
	v_add_u32_e32 v5, v5, v6
	v_and_b32_e32 v6, 63, v5
	v_mul_lo_u32 v5, v5, 25
	v_sub_u32_e32 v5, v4, v5
	s_add_i32 s70, s67, 8
	v_min_i32_e32 v5, 23, v5
	v_mul_u32_u24_e32 v6, 0xc00, v6
	s_cmp_lt_i32 s67, 17
	s_cselect_b64 s[48:49], -1, 0
	s_cmp_gt_i32 s67, 16
	v_lshl_add_u32 v182, v5, 4, v6
	s_cbranch_scc1 .LBB0_2139
	v_mov_b32_e32 v183, v1
	s_lshl_b32 s3, s70, 10
	v_lshl_add_u64 v[6:7], s[34:35], 0, v[182:183]
	s_mov_b32 m0, s3
	s_nop 0
	global_load_lds_dwordx4 v[6:7], off
.LBB0_2139:
	v_add_u32_e32 v5, 0x400, v3
	v_mul_hi_i32 v6, v5, s26
	v_lshrrev_b32_e32 v7, 31, v6
	v_ashrrev_i32_e32 v6, 3, v6
	v_add_u32_e32 v6, v6, v7
	v_and_b32_e32 v7, 63, v6
	v_mul_lo_u32 v6, v6, 25
	v_sub_u32_e32 v6, v5, v6
	s_add_i32 s71, s67, 16
	v_min_i32_e32 v6, 23, v6
	v_mul_u32_u24_e32 v7, 0xc00, v7
	s_cmp_lt_i32 s67, 9
	s_cselect_b64 s[50:51], -1, 0
	s_cmp_gt_i32 s67, 8
	v_lshl_add_u32 v184, v6, 4, v7
	s_cbranch_scc1 .LBB0_2141
	v_mov_b32_e32 v185, v1
	s_lshl_b32 s3, s71, 10
	v_lshl_add_u64 v[6:7], s[34:35], 0, v[184:185]
	s_mov_b32 m0, s3
	s_nop 0
	global_load_lds_dwordx4 v[6:7], off
.LBB0_2141:
	v_add_u32_e32 v6, 0x600, v3
	v_mul_hi_i32 v7, v6, s26
	v_lshrrev_b32_e32 v8, 31, v7
	v_ashrrev_i32_e32 v7, 3, v7
	v_add_u32_e32 v7, v7, v8
	v_and_b32_e32 v8, 63, v7
	v_mul_lo_u32 v7, v7, 25
	v_sub_u32_e32 v6, v6, v7
	s_add_i32 s58, s67, 24
	v_min_i32_e32 v6, 23, v6
	v_mul_u32_u24_e32 v7, 0xc00, v8
	s_cmp_lt_i32 s67, 1
	s_cselect_b64 s[12:13], -1, 0
	s_cmp_gt_i32 s67, 0
	v_lshl_add_u32 v190, v6, 4, v7
	s_cbranch_scc1 .LBB0_2143
	v_mov_b32_e32 v191, v1
	s_lshl_b32 s3, s58, 10
	v_lshl_add_u64 v[6:7], s[34:35], 0, v[190:191]
	s_mov_b32 m0, s3
	s_nop 0
	global_load_lds_dwordx4 v[6:7], off
.LBB0_2143:
	v_mul_hi_i32 v6, v3, s27
	v_lshrrev_b32_e32 v7, 31, v6
	v_ashrrev_i32_e32 v6, 3, v6
	v_add_u32_e32 v6, v6, v7
	v_mul_lo_u32 v7, v6, 20
	v_sub_u32_e32 v3, v3, v7
	v_lshlrev_b32_e32 v6, 11, v6
	s_cmp_lt_i32 s67, 20
	v_and_b32_e32 v6, 0x1f800, v6
	v_min_i32_e32 v3, 15, v3
	s_cselect_b64 s[52:53], -1, 0
	v_lshl_add_u32 v186, v3, 4, v6
	s_and_b64 vcc, exec, s[52:53]
	s_cbranch_vccz .LBB0_2145
	s_lshl_b32 s3, s67, 10
	v_mov_b32_e32 v187, v1
	s_add_i32 s3, s3, 0
	v_lshl_add_u64 v[6:7], s[36:37], 0, v[186:187]
	s_add_i32 s3, s3, 0xc800
	s_mov_b32 m0, s3
	s_nop 0
	global_load_lds_dwordx4 v[6:7], off
.LBB0_2145:
	v_mul_hi_i32 v3, v4, s27
	v_lshrrev_b32_e32 v6, 31, v3
	v_ashrrev_i32_e32 v3, 3, v3
	v_add_u32_e32 v3, v3, v6
	v_mul_lo_u32 v6, v3, 20
	v_sub_u32_e32 v4, v4, v6
	v_lshlrev_b32_e32 v3, 11, v3
	v_and_b32_e32 v3, 0x1f800, v3
	v_min_i32_e32 v4, 15, v4
	s_cmp_lt_i32 s67, 12
	s_cselect_b64 s[54:55], -1, 0
	s_cmp_gt_i32 s67, 11
	v_lshl_add_u32 v188, v4, 4, v3
	s_cbranch_scc1 .LBB0_2147
	s_lshl_b32 s3, s70, 10
	v_mov_b32_e32 v189, v1
	s_add_i32 s3, s3, 0
	v_lshl_add_u64 v[6:7], s[36:37], 0, v[188:189]
	s_add_i32 s3, s3, 0xc800
	s_mov_b32 m0, s3
	s_nop 0
	global_load_lds_dwordx4 v[6:7], off
.LBB0_2147:
	v_mul_hi_i32 v3, v5, s27
	v_lshrrev_b32_e32 v4, 31, v3
	v_ashrrev_i32_e32 v3, 3, v3
	v_add_u32_e32 v3, v3, v4
	v_mul_lo_u32 v4, v3, 20
	v_sub_u32_e32 v4, v5, v4
	v_lshlrev_b32_e32 v3, 11, v3
	v_and_b32_e32 v3, 0x1f800, v3
	v_min_i32_e32 v4, 15, v4
	s_cmp_gt_i32 s67, 3
	v_lshl_add_u32 v192, v4, 4, v3
	s_cbranch_scc1 .LBB0_2149
	s_lshl_b32 s3, s71, 10
	v_mov_b32_e32 v193, v1
	s_add_i32 s3, s3, 0
	v_lshl_add_u64 v[4:5], s[36:37], 0, v[192:193]
	s_add_i32 s3, s3, 0xc800
	s_mov_b32 m0, s3
	s_nop 0
	global_load_lds_dwordx4 v[4:5], off

; template <int DQK>
; __device__ __forceinline__ void attn_pass4(LAS unsigned char* lds, const bf16* Qp, int qpitch, const bf16* Kp, int kpitch, const bf16* Vp, int vpitch, int q0, f32x16 (&o)[4], float (&rl)[16]) {
;     ...
;         for (int t = 0; t < NT; ++t) {
;             const int vnext = ATT_VNEXT(vcur);
;             if (t + 1 < NT) ATT_DMA(t + 1, (t + 1) & 1, vnext);
.LBB0_2151:
	s_add_i32 s61, s78, 1
	s_cmp_lg_u32 s78, 2
	s_cselect_b32 s76, s61, 0
	s_add_i32 s77, s60, 1
	s_cmp_ge_u32 s77, s69
	s_cbranch_scc1 .LBB0_2155_p0
	s_bitcmp1_b32 s77, 0
	s_cselect_b32 s61, 0x6400, 0
	s_add_i32 s62, s61, s2

	s_mov_b32 m0, s62
	s_nop 0
	global_load_lds_dwordx4 v180, s[56:57]
	s_add_i32 s62, s61, s72

	s_mov_b32 m0, s62
	s_nop 0
	global_load_lds_dwordx4 v182, s[56:57]
	s_add_i32 s62, s61, s73

	s_mov_b32 m0, s62
	s_nop 0
	global_load_lds_dwordx4 v184, s[56:57]
	s_andn2_b64 vcc, exec, s[12:13]
	s_cbranch_vccnz .LBB0_2154_p0
	s_add_i32 s61, s61, s74

	s_mov_b32 m0, s61
	s_nop 0
	global_load_lds_dwordx4 v190, s[56:57]
.LBB0_2154_p0:
	s_mul_i32 s61, s76, 0x5000
	s_add_i32 s61, s24, s61

	s_mov_b32 m0, s61
	s_nop 0
	global_load_lds_dwordx4 v186, s[58:59]

	s_add_i32 s62, s61, 0x2000
	s_mov_b32 m0, s62
	s_nop 0
	global_load_lds_dwordx4 v188, s[58:59]
	v_readfirstlane_b32 s32, v242
	s_cmpk_gt_u32 s32, 0xff
	s_cbranch_scc1 .Lskip_v2_2_p0

	s_addk_i32 s61, 0x4000
	s_mov_b32 m0, s61
	s_nop 0
	global_load_lds_dwordx4 v192, s[58:59]

; #define ATT_BAR() asm volatile("s_waitcnt lgkmcnt(0)\n\ts_barrier" ::: "memory")
; #define ATT_BAR() asm volatile("s_waitcnt vmcnt(0) lgkmcnt(0)\n\ts_barrier" ::: "memory")
; template <int DQK>
; __device__ __forceinline__ void attn_pass4(LAS unsigned char* lds, const bf16* Qp, int qpitch, const bf16* Kp, int kpitch, const bf16* Vp, int vpitch, int q0, f32x16 (&o)[4], float (&rl)[16]) {
;     ...
;         for (int t = 0; t < NT; ++t) {
;             const int vnext = ATT_VNEXT(vcur);
;             if (t + 1 < NT) ATT_DMA(t + 1, (t + 1) & 1, vnext);
;             if (ATT_VIS(t)) { ATT_A(t); ATT_B(vcur); }
;             vcur = vnext;
;             ATT_BAR();
.Lend_ba:
	s_add_i32 s75, s75, 64
	s_add_u32 s58, s58, 0x20000
	s_addc_u32 s59, s59, 0
	s_add_u32 s56, s56, 0x30000
	s_waitcnt vmcnt(0) lgkmcnt(0)
	s_barrier
	s_addc_u32 s57, s57, 0
	s_cmp_eq_u32 s69, s77
	s_mov_b32 s93, s78
	s_mov_b32 s78, s76
	s_mov_b32 s60, s77
	s_add_i32 s61, s78, 1
	s_cmp_lg_u32 s78, 2
	s_cselect_b32 s76, s61, 0
	s_add_i32 s77, s60, 1
	s_cmp_ge_u32 s77, s69
	s_cbranch_scc1 .LBB0_2155_ab
	s_bitcmp1_b32 s77, 0
	s_cselect_b32 s61, 0x6400, 0
	s_add_i32 s62, s61, s2

	s_mov_b32 m0, s62
	s_nop 0
	global_load_lds_dwordx4 v180, s[56:57]
	s_add_i32 s62, s61, s72

	s_mov_b32 m0, s62
	s_nop 0
	global_load_lds_dwordx4 v182, s[56:57]
	s_add_i32 s62, s61, s73

	s_mov_b32 m0, s62
	s_nop 0
	global_load_lds_dwordx4 v184, s[56:57]
	s_andn2_b64 vcc, exec, s[12:13]
	s_cbranch_vccnz .LBB0_2154_ab
	s_add_i32 s61, s61, s74

	s_mov_b32 m0, s61
	s_nop 0
	global_load_lds_dwordx4 v190, s[56:57]

; #define ATT_BAR() asm volatile("s_waitcnt lgkmcnt(0)\n\ts_barrier" ::: "memory")
; #define ATT_BAR() asm volatile("s_waitcnt vmcnt(0) lgkmcnt(0)\n\ts_barrier" ::: "memory")
; template <int DQK>
; __device__ __forceinline__ void attn_pass4(LAS unsigned char* lds, const bf16* Qp, int qpitch, const bf16* Kp, int kpitch, const bf16* Vp, int vpitch, int q0, f32x16 (&o)[4], float (&rl)[16]) {
;     ...
;         for (int t = 0; t < NT; ++t) {
;             const int vnext = ATT_VNEXT(vcur);
;             if (t + 1 < NT) ATT_DMA(t + 1, (t + 1) & 1, vnext);
;             if (ATT_VIS(t)) { ATT_A(t); ATT_B(vcur); }
;             vcur = vnext;
;             ATT_BAR();
.Lend_ab:
	s_add_i32 s75, s75, 64
	s_add_u32 s58, s58, 0x20000
	s_addc_u32 s59, s59, 0
	s_add_u32 s56, s56, 0x30000
	s_waitcnt vmcnt(0) lgkmcnt(0)
	s_barrier
	s_addc_u32 s57, s57, 0
	s_cmp_eq_u32 s69, s77
	s_mov_b32 s93, s78
	s_mov_b32 s78, s76
	s_mov_b32 s60, s77
	s_add_i32 s61, s77, 1
	s_cmp_eq_u32 s61, s69
	s_cbranch_scc0 .Lpipe_loop
	s_add_i32 s61, s78, 1
	s_cmp_lg_u32 s78, 2
	s_cselect_b32 s76, s61, 0
	s_add_i32 s77, s60, 1
	s_cmp_ge_u32 s77, s69
	s_cbranch_scc1 .LBB0_2155_fin
	s_bitcmp1_b32 s77, 0
	s_cselect_b32 s61, 0x6400, 0
	s_add_i32 s62, s61, s2

	s_mov_b32 m0, s62
	s_nop 0
	global_load_lds_dwordx4 v180, s[56:57]
	s_add_i32 s62, s61, s72

	s_mov_b32 m0, s62
	s_nop 0
	global_load_lds_dwordx4 v182, s[56:57]
	s_add_i32 s62, s61, s73

	s_mov_b32 m0, s62
	s_nop 0
	global_load_lds_dwordx4 v184, s[56:57]
	s_andn2_b64 vcc, exec, s[12:13]
	s_cbranch_vccnz .LBB0_2154_fin
	s_add_i32 s61, s61, s74

	s_mov_b32 m0, s61
	s_nop 0
	global_load_lds_dwordx4 v190, s[56:57]

; template <int DQK>
; __device__ __forceinline__ void attn_pass4(LAS unsigned char* lds, const bf16* Qp, int qpitch, const bf16* Kp, int kpitch, const bf16* Vp, int vpitch, int q0, f32x16 (&o)[4], float (&rl)[16]) {
;     ...
;         for (int t = 0; t < NT; ++t) {
;             const int vnext = ATT_VNEXT(vcur);
;             if (t + 1 < NT) ATT_DMA(t + 1, (t + 1) & 1, vnext);
.LBB0_2180:
	s_add_i32 s24, s24, s63
	v_lshl_add_u64 v[4:5], s[58:59], 0, v[188:189]
	s_mov_b32 m0, s24
	s_nop 0
	global_load_lds_dwordx4 v[4:5], off

; template <int DQK>
; __device__ __forceinline__ void attn_pass4(LAS unsigned char* lds, const bf16* Qp, int qpitch, const bf16* Kp, int kpitch, const bf16* Vp, int vpitch, int q0, f32x16 (&o)[4], float (&rl)[16]) {
;     ...
;         for (int t = 0; t < NT; ++t) {
;             const int vnext = ATT_VNEXT(vcur);
;             if (t + 1 < NT) ATT_DMA(t + 1, (t + 1) & 1, vnext);
.LBB0_2192:
	s_add_i32 s25, s24, s62
	v_lshl_add_u64 v[4:5], s[56:57], 0, v[180:181]
	s_mov_b32 m0, s25
	s_nop 0
	global_load_lds_dwordx4 v[4:5], off
	s_andn2_b64 vcc, exec, s[48:49]
	s_cbranch_vccnz .LBB0_2177
.LBB0_2193:
	s_add_i32 s25, s24, s63
	v_lshl_add_u64 v[4:5], s[56:57], 0, v[182:183]
	s_mov_b32 m0, s25
	s_nop 0
	global_load_lds_dwordx4 v[4:5], off
	s_andn2_b64 vcc, exec, s[50:51]
	s_cbranch_vccnz .LBB0_2178
.LBB0_2194:
	s_add_i32 s24, s24, s70
	v_lshl_add_u64 v[4:5], s[56:57], 0, v[184:185]
	s_mov_b32 m0, s24
	s_nop 0
	global_load_lds_dwordx4 v[4:5], off
	s_mul_i32 s24, s72, 0x5000
	s_andn2_b64 vcc, exec, s[52:53]
	s_add_i32 s24, s24, 0xc800
	s_cbranch_vccnz .LBB0_2179
.LBB0_2195:
	s_add_i32 s25, s24, s62
	v_lshl_add_u64 v[4:5], s[58:59], 0, v[186:187]
	s_mov_b32 m0, s25
	s_nop 0
	global_load_lds_dwordx4 v[4:5], off
	s_andn2_b64 vcc, exec, s[54:55]
	s_cbranch_vccz .LBB0_2180
	s_branch .LBB0_2181
